# code placement pin also on the conv tap loop head (on top of v42)
# baseline (speedup 1.0000x reference)
; __device__ __forceinline__ void conv_item(KP p, LAS unsigned char* lds, int l, int tile) {
;     ...
;     for (int hh = 0; hh < 2; ++hh) {
;     const int t0 = tbase + hh * 32;
; #pragma unroll 1
;     for (int blk = 0; blk < 8; ++blk) {
.LBB0_461:
	s_or_b32 s6, s63, s25
	s_xor_b64 s[40:41], s[44:45], -1
	s_add_i32 s44, s25, 60
	s_add_i32 s45, s47, s63
	s_mov_b32 s64, 0
	.p2align 6
